# gMLP unit: the four cold u-row loads of the output stage are issued before the mixing MFMAs (were four load->wait->store round trips)
# speedup vs baseline: 1.0099x; 1.0009x over previous
.LBB0_605:
	s_cmpk_gt_u32 s28, 0x94f
	s_mov_b64 s[2:3], -1
	s_cbranch_scc1 .LBB0_429
	s_add_i32 s4, s28, 0xfffffad0
	s_lshr_b32 s2, s4, 2
	s_mul_i32 s3, s2, 0xf83f
	s_lshr_b32 s3, s3, 22
	s_mulk_i32 s3, 0x42
	s_sub_i32 s2, s2, s3
	s_and_b32 s3, s2, 0xffff
	s_cmp_lt_u32 s3, 2
	v_readlane_b32 s8, v254, 51
	s_cselect_b64 s[6:7], -1, 0
	v_readlane_b32 s9, v254, 52
	s_and_b64 s[6:7], s[8:9], s[6:7]
	s_and_b64 vcc, exec, s[6:7]
	s_cbranch_vccnz .LBB0_428
	s_mul_i32 s3, s4, 0xf83f
	s_lshr_b32 s3, s3, 24
	s_pack_ll_b32_b16 s2, s2, s3
	v_mov_b32_e32 v18, v196
	v_pk_mul_lo_u16 v0, s2, v210
	s_mov_b32 s2, 27
	s_ashr_i32 s3, s2, 31
	s_lshl_b64 s[2:3], s[2:3], 3
	s_add_u32 s2, s0, s2
	s_addc_u32 s3, s1, s3
	s_load_dwordx2 s[8:9], s[2:3], 0x0
	s_mov_b32 s2, 27
	s_ashr_i32 s3, s2, 31
	s_lshl_b64 s[2:3], s[2:3], 3
	s_add_u32 s2, s0, s2
	v_add_u32_sdwa v0, v0, v0 dst_sel:DWORD dst_unused:UNUSED_PAD src0_sel:DWORD src1_sel:WORD_1
	s_addc_u32 s3, s1, s3
	v_ashrrev_i32_e32 v26, 2, v18
	v_and_b32_e32 v0, 0xff80, v0
	s_lshl_b32 s4, s4, 7
	v_add_u32_e32 v32, v26, v0
	s_waitcnt lgkmcnt(0)
	v_mov_b64_e32 v[2:3], s[8:9]
	s_and_b32 s7, s4, 0x180
	v_lshlrev_b32_e32 v0, 5, v18
	v_mad_i64_i32 v[2:3], s[8:9], v32, s33, v[2:3]
	s_lshl_b32 s46, s7, 1
	v_and_b32_e32 v19, 0x60, v0
	v_lshl_add_u64 v[2:3], v[2:3], 0, s[46:47]
	v_lshlrev_b32_e32 v0, 1, v19
	v_lshl_add_u64 v[24:25], v[2:3], 0, v[0:1]
	s_mov_b64 s[4:5], 0x7c00000
	v_lshl_add_u64 v[22:23], v[24:25], 0, s[4:5]
	s_load_dwordx2 s[2:3], s[2:3], 0x0
	global_load_dwordx4 v[2:5], v[22:23], off offset:1072
	global_load_dwordx4 v[6:9], v[22:23], off offset:1056
	global_load_dwordx4 v[10:13], v[22:23], off offset:1040
	global_load_dwordx4 v[14:17], v[22:23], off offset:1024
	s_mov_b32 s4, 11
	s_ashr_i32 s5, s4, 31
	s_lshl_b64 s[4:5], s[4:5], 3
	s_add_u32 s4, s0, s4
	s_addc_u32 s5, s1, s5
	s_load_dwordx2 s[4:5], s[4:5], 0x0
	v_readlane_b32 s8, v252, 21
	v_readlane_b32 s9, v252, 22
	v_lshlrev_b32_e32 v62, 1, v26
	v_readfirstlane_b32 s6, v18
	s_waitcnt lgkmcnt(0)
	s_add_u32 s4, s4, s8
	s_addc_u32 s5, s5, s9
	s_lshl_b32 s8, s7, 2
	s_add_u32 s4, s4, s8
	s_addc_u32 s5, s5, 0
	v_and_b32_e32 v31, 63, v18
	s_waitcnt vmcnt(0)
	v_lshlrev_b32_e32 v20, 16, v14
	v_mul_f32_e32 v21, 0x3d372713, v20
	v_mul_f32_e32 v21, v21, v20
	v_fma_f32 v21, v21, v20, v20
	v_mul_f32_e32 v21, 0x3f4c422a, v21
	v_add_f32_e32 v21, v21, v21
	v_mul_f32_e32 v21, 0x3fb8aa3b, v21
	v_exp_f32_e32 v21, v21
	v_mul_f32_e32 v20, 0.5, v20
	v_and_b32_e32 v14, 0xffff0000, v14
	v_add_f32_e32 v21, 1.0, v21
	v_rcp_f32_e32 v21, v21
	s_nop 0
	v_fma_f32 v21, v21, -2.0, 1.0
	v_add_f32_e32 v21, 1.0, v21
	v_mul_f32_e32 v20, v20, v21
	v_mul_f32_e32 v21, 0x3d372713, v14
	v_mul_f32_e32 v21, v21, v14
	v_fma_f32 v21, v21, v14, v14
	v_mul_f32_e32 v21, 0x3f4c422a, v21
	v_add_f32_e32 v21, v21, v21
	v_mul_f32_e32 v21, 0x3fb8aa3b, v21
	v_exp_f32_e32 v21, v21
	v_mul_f32_e32 v14, 0.5, v14
	v_add_f32_e32 v21, 1.0, v21
	v_rcp_f32_e32 v21, v21
	s_nop 0
	v_fma_f32 v21, v21, -2.0, 1.0
	v_add_f32_e32 v21, 1.0, v21
	v_mul_f32_e32 v14, v14, v21
	v_lshlrev_b32_e32 v21, 16, v15
	v_mul_f32_e32 v28, 0x3d372713, v21
	v_mul_f32_e32 v28, v28, v21
	v_fma_f32 v28, v28, v21, v21
	v_mul_f32_e32 v28, 0x3f4c422a, v28
	v_add_f32_e32 v28, v28, v28
	v_mul_f32_e32 v28, 0x3fb8aa3b, v28
	v_exp_f32_e32 v28, v28
	v_mul_f32_e32 v21, 0.5, v21
	v_and_b32_e32 v15, 0xffff0000, v15
	v_mul_f32_e32 v27, v14, v14
	v_add_f32_e32 v28, 1.0, v28
	v_rcp_f32_e32 v28, v28
	v_fmac_f32_e32 v27, v20, v20
	v_fma_f32 v28, v28, -2.0, 1.0
	v_add_f32_e32 v28, 1.0, v28
	v_mul_f32_e32 v21, v21, v28
	v_mul_f32_e32 v28, 0x3d372713, v15
	v_mul_f32_e32 v28, v28, v15
	v_fma_f32 v28, v28, v15, v15
	v_mul_f32_e32 v28, 0x3f4c422a, v28
	v_add_f32_e32 v28, v28, v28
	v_mul_f32_e32 v28, 0x3fb8aa3b, v28
	v_exp_f32_e32 v28, v28
	v_mul_f32_e32 v15, 0.5, v15
	v_add_f32_e32 v28, 1.0, v28
	v_rcp_f32_e32 v28, v28
	s_nop 0
	v_fma_f32 v28, v28, -2.0, 1.0
	v_add_f32_e32 v28, 1.0, v28
	v_mul_f32_e32 v15, v15, v28
	v_mul_f32_e32 v28, v15, v15
	v_fmac_f32_e32 v28, v21, v21
	v_add_f32_e32 v28, v27, v28
	v_lshlrev_b32_e32 v27, 16, v16
	v_mul_f32_e32 v29, 0x3d372713, v27
	v_mul_f32_e32 v29, v29, v27
	v_fma_f32 v29, v29, v27, v27
	v_mul_f32_e32 v29, 0x3f4c422a, v29
	v_add_f32_e32 v29, v29, v29
	v_mul_f32_e32 v29, 0x3fb8aa3b, v29
	v_exp_f32_e32 v29, v29
	v_mul_f32_e32 v27, 0.5, v27
	v_and_b32_e32 v16, 0xffff0000, v16
	v_add_f32_e32 v29, 1.0, v29
	v_rcp_f32_e32 v29, v29
	s_nop 0
	v_fma_f32 v29, v29, -2.0, 1.0
	v_add_f32_e32 v29, 1.0, v29
	v_mul_f32_e32 v27, v27, v29
	v_mul_f32_e32 v29, 0x3d372713, v16
	v_mul_f32_e32 v29, v29, v16
	v_fma_f32 v29, v29, v16, v16
	v_mul_f32_e32 v29, 0x3f4c422a, v29
	v_add_f32_e32 v29, v29, v29
	v_mul_f32_e32 v29, 0x3fb8aa3b, v29
	v_exp_f32_e32 v29, v29
	v_mul_f32_e32 v16, 0.5, v16
	v_add_f32_e32 v29, 1.0, v29
	v_rcp_f32_e32 v29, v29
	s_nop 0
	v_fma_f32 v29, v29, -2.0, 1.0
	v_add_f32_e32 v29, 1.0, v29
	v_mul_f32_e32 v16, v16, v29
	v_mul_f32_e32 v29, v16, v16
	v_fmac_f32_e32 v29, v27, v27
	v_add_f32_e32 v28, v29, v28
	v_lshlrev_b32_e32 v29, 16, v17
	v_mul_f32_e32 v30, 0x3d372713, v29
	v_mul_f32_e32 v30, v30, v29
	v_fma_f32 v30, v30, v29, v29
	v_mul_f32_e32 v30, 0x3f4c422a, v30
	v_add_f32_e32 v30, v30, v30
	v_mul_f32_e32 v30, 0x3fb8aa3b, v30
	v_exp_f32_e32 v30, v30
	v_mul_f32_e32 v29, 0.5, v29
	v_and_b32_e32 v17, 0xffff0000, v17
	v_add_f32_e32 v30, 1.0, v30
	v_rcp_f32_e32 v30, v30
	s_nop 0
	v_fma_f32 v30, v30, -2.0, 1.0
	v_add_f32_e32 v30, 1.0, v30
	v_mul_f32_e32 v39, v29, v30
	v_mul_f32_e32 v29, 0x3d372713, v17
	v_mul_f32_e32 v29, v29, v17
	v_fma_f32 v29, v29, v17, v17
	v_mul_f32_e32 v29, 0x3f4c422a, v29
	v_add_f32_e32 v29, v29, v29
	v_mul_f32_e32 v29, 0x3fb8aa3b, v29
	v_exp_f32_e32 v29, v29
	v_mul_f32_e32 v17, 0.5, v17
	v_add_f32_e32 v29, 1.0, v29
	v_rcp_f32_e32 v29, v29
	s_nop 0
	v_fma_f32 v29, v29, -2.0, 1.0
	v_add_f32_e32 v29, 1.0, v29
	v_mul_f32_e32 v17, v17, v29
	v_mul_f32_e32 v29, v17, v17
	v_fmac_f32_e32 v29, v39, v39
	v_add_f32_e32 v28, v29, v28
	v_lshlrev_b32_e32 v29, 16, v10
	v_mul_f32_e32 v30, 0x3d372713, v29
	v_mul_f32_e32 v30, v30, v29
	v_fma_f32 v30, v30, v29, v29
	v_mul_f32_e32 v30, 0x3f4c422a, v30
	v_add_f32_e32 v30, v30, v30
	v_mul_f32_e32 v30, 0x3fb8aa3b, v30
	v_exp_f32_e32 v30, v30
	v_mul_f32_e32 v29, 0.5, v29
	v_and_b32_e32 v10, 0xffff0000, v10
	v_add_f32_e32 v30, 1.0, v30
	v_rcp_f32_e32 v30, v30
	s_nop 0
	v_fma_f32 v30, v30, -2.0, 1.0
	v_add_f32_e32 v30, 1.0, v30
	v_mul_f32_e32 v42, v29, v30
	v_mul_f32_e32 v29, 0x3d372713, v10
	v_mul_f32_e32 v29, v29, v10
	v_fma_f32 v29, v29, v10, v10
	v_mul_f32_e32 v29, 0x3f4c422a, v29
	v_add_f32_e32 v29, v29, v29
	v_mul_f32_e32 v29, 0x3fb8aa3b, v29
	v_exp_f32_e32 v29, v29
	v_mul_f32_e32 v10, 0.5, v10
	v_add_f32_e32 v29, 1.0, v29
	v_rcp_f32_e32 v29, v29
	s_nop 0
	v_fma_f32 v29, v29, -2.0, 1.0
	v_add_f32_e32 v29, 1.0, v29
	v_mul_f32_e32 v10, v10, v29
	v_mul_f32_e32 v29, v10, v10
	v_fmac_f32_e32 v29, v42, v42
	v_add_f32_e32 v28, v29, v28
	v_lshlrev_b32_e32 v29, 16, v11
	v_mul_f32_e32 v30, 0x3d372713, v29
	v_mul_f32_e32 v30, v30, v29
	v_fma_f32 v30, v30, v29, v29
	v_mul_f32_e32 v30, 0x3f4c422a, v30
	v_add_f32_e32 v30, v30, v30
	v_mul_f32_e32 v30, 0x3fb8aa3b, v30
	v_exp_f32_e32 v30, v30
	v_mul_f32_e32 v29, 0.5, v29
	v_and_b32_e32 v11, 0xffff0000, v11
	v_add_f32_e32 v30, 1.0, v30
	v_rcp_f32_e32 v30, v30
	s_nop 0
	v_fma_f32 v30, v30, -2.0, 1.0
	v_add_f32_e32 v30, 1.0, v30
	v_mul_f32_e32 v45, v29, v30
	v_mul_f32_e32 v29, 0x3d372713, v11
	v_mul_f32_e32 v29, v29, v11
	v_fma_f32 v29, v29, v11, v11
	v_mul_f32_e32 v29, 0x3f4c422a, v29
	v_add_f32_e32 v29, v29, v29
	v_mul_f32_e32 v29, 0x3fb8aa3b, v29
	v_exp_f32_e32 v29, v29
	v_mul_f32_e32 v11, 0.5, v11
	v_add_f32_e32 v29, 1.0, v29
	v_rcp_f32_e32 v29, v29
	s_nop 0
	v_fma_f32 v29, v29, -2.0, 1.0
	v_add_f32_e32 v29, 1.0, v29
	v_mul_f32_e32 v11, v11, v29
	v_mul_f32_e32 v29, v11, v11
	v_fmac_f32_e32 v29, v45, v45
	v_add_f32_e32 v28, v29, v28
	v_lshlrev_b32_e32 v29, 16, v12
	v_mul_f32_e32 v30, 0x3d372713, v29
	v_mul_f32_e32 v30, v30, v29
	v_fma_f32 v30, v30, v29, v29
	v_mul_f32_e32 v30, 0x3f4c422a, v30
	v_add_f32_e32 v30, v30, v30
	v_mul_f32_e32 v30, 0x3fb8aa3b, v30
	v_exp_f32_e32 v30, v30
	v_mul_f32_e32 v29, 0.5, v29
	v_and_b32_e32 v12, 0xffff0000, v12
	v_add_f32_e32 v30, 1.0, v30
	v_rcp_f32_e32 v30, v30
	s_nop 0
	v_fma_f32 v30, v30, -2.0, 1.0
	v_add_f32_e32 v30, 1.0, v30
	v_mul_f32_e32 v50, v29, v30
	v_mul_f32_e32 v29, 0x3d372713, v12
	v_mul_f32_e32 v29, v29, v12
	v_fma_f32 v29, v29, v12, v12
	v_mul_f32_e32 v29, 0x3f4c422a, v29
	v_add_f32_e32 v29, v29, v29
	v_mul_f32_e32 v29, 0x3fb8aa3b, v29
	v_exp_f32_e32 v29, v29
	v_mul_f32_e32 v12, 0.5, v12
	v_add_f32_e32 v29, 1.0, v29
	v_rcp_f32_e32 v29, v29
	s_nop 0
	v_fma_f32 v29, v29, -2.0, 1.0
	v_add_f32_e32 v29, 1.0, v29
	v_mul_f32_e32 v12, v12, v29
	v_mul_f32_e32 v29, v12, v12
	v_fmac_f32_e32 v29, v50, v50
	v_add_f32_e32 v28, v29, v28
	v_lshlrev_b32_e32 v29, 16, v13
	v_mul_f32_e32 v30, 0x3d372713, v29
	v_mul_f32_e32 v30, v30, v29
	v_fma_f32 v30, v30, v29, v29
	v_mul_f32_e32 v30, 0x3f4c422a, v30
	v_add_f32_e32 v30, v30, v30
	v_mul_f32_e32 v30, 0x3fb8aa3b, v30
	v_exp_f32_e32 v30, v30
	v_mul_f32_e32 v29, 0.5, v29
	v_and_b32_e32 v13, 0xffff0000, v13
	v_add_f32_e32 v30, 1.0, v30
	v_rcp_f32_e32 v30, v30
	s_nop 0
	v_fma_f32 v30, v30, -2.0, 1.0
	v_add_f32_e32 v30, 1.0, v30
	v_mul_f32_e32 v52, v29, v30
	v_mul_f32_e32 v29, 0x3d372713, v13
	v_mul_f32_e32 v29, v29, v13
	v_fma_f32 v29, v29, v13, v13
	v_mul_f32_e32 v29, 0x3f4c422a, v29
	v_add_f32_e32 v29, v29, v29
	v_mul_f32_e32 v29, 0x3fb8aa3b, v29
	v_exp_f32_e32 v29, v29
	v_mul_f32_e32 v13, 0.5, v13
	v_add_f32_e32 v29, 1.0, v29
	v_rcp_f32_e32 v29, v29
	s_nop 0
	v_fma_f32 v29, v29, -2.0, 1.0
	v_add_f32_e32 v29, 1.0, v29
	v_mul_f32_e32 v13, v13, v29
	v_mul_f32_e32 v29, v13, v13
	v_fmac_f32_e32 v29, v52, v52
	v_add_f32_e32 v28, v29, v28
	v_lshlrev_b32_e32 v29, 16, v6
	v_mul_f32_e32 v30, 0x3d372713, v29
	v_mul_f32_e32 v30, v30, v29
	v_fma_f32 v30, v30, v29, v29
	v_mul_f32_e32 v30, 0x3f4c422a, v30
	v_add_f32_e32 v30, v30, v30
	v_mul_f32_e32 v30, 0x3fb8aa3b, v30
	v_exp_f32_e32 v30, v30
	v_mul_f32_e32 v29, 0.5, v29
	v_and_b32_e32 v6, 0xffff0000, v6
	v_add_f32_e32 v30, 1.0, v30
	v_rcp_f32_e32 v30, v30
	s_nop 0
	v_fma_f32 v30, v30, -2.0, 1.0
	v_add_f32_e32 v30, 1.0, v30
	v_mul_f32_e32 v53, v29, v30
	v_mul_f32_e32 v29, 0x3d372713, v6
	v_mul_f32_e32 v29, v29, v6
	v_fma_f32 v29, v29, v6, v6
	v_mul_f32_e32 v29, 0x3f4c422a, v29
	v_add_f32_e32 v29, v29, v29
	v_mul_f32_e32 v29, 0x3fb8aa3b, v29
	v_exp_f32_e32 v29, v29
	v_mul_f32_e32 v6, 0.5, v6
	v_add_f32_e32 v29, 1.0, v29
	v_rcp_f32_e32 v29, v29
	s_nop 0
	v_fma_f32 v29, v29, -2.0, 1.0
	v_add_f32_e32 v29, 1.0, v29
	v_mul_f32_e32 v30, v6, v29
	v_mul_f32_e32 v6, v30, v30
	v_fmac_f32_e32 v6, v53, v53
	v_add_f32_e32 v6, v6, v28
	v_lshlrev_b32_e32 v28, 16, v7
	v_mul_f32_e32 v29, 0x3d372713, v28
	v_mul_f32_e32 v29, v29, v28
	v_fma_f32 v29, v29, v28, v28
	v_mul_f32_e32 v29, 0x3f4c422a, v29
	v_add_f32_e32 v29, v29, v29
	v_mul_f32_e32 v29, 0x3fb8aa3b, v29
	v_exp_f32_e32 v29, v29
	v_mul_f32_e32 v28, 0.5, v28
	v_and_b32_e32 v7, 0xffff0000, v7
	v_add_f32_e32 v29, 1.0, v29
	v_rcp_f32_e32 v29, v29
	s_nop 0
	v_fma_f32 v29, v29, -2.0, 1.0
	v_add_f32_e32 v29, 1.0, v29
	v_mul_f32_e32 v33, v28, v29
	v_mul_f32_e32 v28, 0x3d372713, v7
	v_mul_f32_e32 v28, v28, v7
	v_fma_f32 v28, v28, v7, v7
	v_mul_f32_e32 v28, 0x3f4c422a, v28
	v_add_f32_e32 v28, v28, v28
	v_mul_f32_e32 v28, 0x3fb8aa3b, v28
	v_exp_f32_e32 v28, v28
	v_mul_f32_e32 v7, 0.5, v7
	v_mov_b32_e32 v29, v1
	v_add_f32_e32 v28, 1.0, v28
	v_rcp_f32_e32 v28, v28
	s_nop 0
	v_fma_f32 v28, v28, -2.0, 1.0
	v_add_f32_e32 v28, 1.0, v28
	v_mul_f32_e32 v34, v7, v28
	v_mul_f32_e32 v7, v34, v34
	v_fmac_f32_e32 v7, v33, v33
	v_add_f32_e32 v6, v7, v6
	v_lshlrev_b32_e32 v7, 16, v8
	v_mul_f32_e32 v28, 0x3d372713, v7
	v_mul_f32_e32 v28, v28, v7
	v_fma_f32 v28, v28, v7, v7
	v_mul_f32_e32 v28, 0x3f4c422a, v28
	v_add_f32_e32 v28, v28, v28
	v_mul_f32_e32 v28, 0x3fb8aa3b, v28
	v_exp_f32_e32 v28, v28
	v_mul_f32_e32 v7, 0.5, v7
	v_add_f32_e32 v28, 1.0, v28
	v_rcp_f32_e32 v28, v28
	s_nop 0
	v_fma_f32 v28, v28, -2.0, 1.0
	v_add_f32_e32 v28, 1.0, v28
	v_mul_f32_e32 v35, v7, v28
	v_and_b32_e32 v7, 0xffff0000, v8
	v_mul_f32_e32 v8, 0x3d372713, v7
	v_mul_f32_e32 v8, v8, v7
	v_fma_f32 v8, v8, v7, v7
	v_mul_f32_e32 v8, 0x3f4c422a, v8
	v_add_f32_e32 v8, v8, v8
	v_mul_f32_e32 v8, 0x3fb8aa3b, v8
	v_exp_f32_e32 v8, v8
	v_mul_f32_e32 v7, 0.5, v7
	v_lshlrev_b32_e32 v28, 2, v19
	v_mul_u32_u24_e32 v19, 0x110, v19
	v_add_f32_e32 v8, 1.0, v8
	v_rcp_f32_e32 v8, v8
	v_add3_u32 v19, 0, v62, v19
	v_fma_f32 v8, v8, -2.0, 1.0
	v_add_f32_e32 v8, 1.0, v8
	v_mul_f32_e32 v36, v7, v8
	v_mul_f32_e32 v7, v36, v36
	v_fmac_f32_e32 v7, v35, v35
	v_add_f32_e32 v6, v7, v6
	v_lshlrev_b32_e32 v7, 16, v9
	v_mul_f32_e32 v8, 0x3d372713, v7
	v_mul_f32_e32 v8, v8, v7
	v_fma_f32 v8, v8, v7, v7
	v_mul_f32_e32 v8, 0x3f4c422a, v8
	v_add_f32_e32 v8, v8, v8
	v_mul_f32_e32 v8, 0x3fb8aa3b, v8
	v_exp_f32_e32 v8, v8
	v_mul_f32_e32 v7, 0.5, v7
	v_add_f32_e32 v8, 1.0, v8
	v_rcp_f32_e32 v8, v8
	s_nop 0
	v_fma_f32 v8, v8, -2.0, 1.0
	v_add_f32_e32 v8, 1.0, v8
	v_mul_f32_e32 v37, v7, v8
	v_and_b32_e32 v7, 0xffff0000, v9
	v_mul_f32_e32 v8, 0x3d372713, v7
	v_mul_f32_e32 v8, v8, v7
	v_fma_f32 v8, v8, v7, v7
	v_mul_f32_e32 v8, 0x3f4c422a, v8
	v_add_f32_e32 v8, v8, v8
	v_mul_f32_e32 v8, 0x3fb8aa3b, v8
	v_exp_f32_e32 v8, v8
	v_mul_f32_e32 v7, 0.5, v7
	v_add_f32_e32 v8, 1.0, v8
	v_rcp_f32_e32 v8, v8
	s_nop 0
	v_fma_f32 v8, v8, -2.0, 1.0
	v_add_f32_e32 v8, 1.0, v8
	v_mul_f32_e32 v38, v7, v8
	v_mul_f32_e32 v7, v38, v38
	v_fmac_f32_e32 v7, v37, v37
	v_add_f32_e32 v6, v7, v6
	v_lshlrev_b32_e32 v7, 16, v2
	v_mul_f32_e32 v8, 0x3d372713, v7
	v_mul_f32_e32 v8, v8, v7
	v_fma_f32 v8, v8, v7, v7
	v_mul_f32_e32 v8, 0x3f4c422a, v8
	v_add_f32_e32 v8, v8, v8
	v_mul_f32_e32 v8, 0x3fb8aa3b, v8
	v_exp_f32_e32 v8, v8
	v_mul_f32_e32 v7, 0.5, v7
	v_and_b32_e32 v2, 0xffff0000, v2
	v_add_f32_e32 v8, 1.0, v8
	v_rcp_f32_e32 v8, v8
	s_nop 0
	v_fma_f32 v8, v8, -2.0, 1.0
	v_add_f32_e32 v8, 1.0, v8
	v_mul_f32_e32 v40, v7, v8
	v_mul_f32_e32 v7, 0x3d372713, v2
	v_mul_f32_e32 v7, v7, v2
	v_fma_f32 v7, v7, v2, v2
	v_mul_f32_e32 v7, 0x3f4c422a, v7
	v_add_f32_e32 v7, v7, v7
	v_mul_f32_e32 v7, 0x3fb8aa3b, v7
	v_exp_f32_e32 v7, v7
	v_mul_f32_e32 v2, 0.5, v2
	v_add_f32_e32 v7, 1.0, v7
	v_rcp_f32_e32 v7, v7
	s_nop 0
	v_fma_f32 v7, v7, -2.0, 1.0
	v_add_f32_e32 v7, 1.0, v7
	v_mul_f32_e32 v41, v2, v7
	v_mul_f32_e32 v2, v41, v41
	v_fmac_f32_e32 v2, v40, v40
	v_add_f32_e32 v2, v2, v6
	v_lshlrev_b32_e32 v6, 16, v3
	v_mul_f32_e32 v7, 0x3d372713, v6
	v_mul_f32_e32 v7, v7, v6
	v_fma_f32 v7, v7, v6, v6
	v_mul_f32_e32 v7, 0x3f4c422a, v7
	v_add_f32_e32 v7, v7, v7
	v_mul_f32_e32 v7, 0x3fb8aa3b, v7
	v_exp_f32_e32 v7, v7
	v_mul_f32_e32 v6, 0.5, v6
	v_and_b32_e32 v3, 0xffff0000, v3
	v_add_f32_e32 v7, 1.0, v7
	v_rcp_f32_e32 v7, v7
	s_nop 0
	v_fma_f32 v7, v7, -2.0, 1.0
	v_add_f32_e32 v7, 1.0, v7
	v_mul_f32_e32 v43, v6, v7
	v_mul_f32_e32 v6, 0x3d372713, v3
	v_mul_f32_e32 v6, v6, v3
	v_fma_f32 v6, v6, v3, v3
	v_mul_f32_e32 v6, 0x3f4c422a, v6
	v_add_f32_e32 v6, v6, v6
	v_mul_f32_e32 v6, 0x3fb8aa3b, v6
	v_exp_f32_e32 v6, v6
	v_mul_f32_e32 v3, 0.5, v3
	v_add_f32_e32 v6, 1.0, v6
	v_rcp_f32_e32 v6, v6
	s_nop 0
	v_fma_f32 v6, v6, -2.0, 1.0
	v_add_f32_e32 v6, 1.0, v6
	v_mul_f32_e32 v44, v3, v6
	v_mul_f32_e32 v3, v44, v44
	v_fmac_f32_e32 v3, v43, v43
	v_add_f32_e32 v2, v3, v2
	v_lshlrev_b32_e32 v3, 16, v4
	v_mul_f32_e32 v6, 0x3d372713, v3
	v_mul_f32_e32 v6, v6, v3
	v_fma_f32 v6, v6, v3, v3
	v_mul_f32_e32 v6, 0x3f4c422a, v6
	v_add_f32_e32 v6, v6, v6
	v_mul_f32_e32 v6, 0x3fb8aa3b, v6
	v_exp_f32_e32 v6, v6
	v_mul_f32_e32 v3, 0.5, v3
	v_add_f32_e32 v6, 1.0, v6
	v_rcp_f32_e32 v6, v6
	s_nop 0
	v_fma_f32 v6, v6, -2.0, 1.0
	v_add_f32_e32 v6, 1.0, v6
	v_mul_f32_e32 v46, v3, v6
	v_and_b32_e32 v3, 0xffff0000, v4
	v_mul_f32_e32 v4, 0x3d372713, v3
	v_mul_f32_e32 v4, v4, v3
	v_fma_f32 v4, v4, v3, v3
	v_mul_f32_e32 v4, 0x3f4c422a, v4
	v_add_f32_e32 v4, v4, v4
	v_mul_f32_e32 v4, 0x3fb8aa3b, v4
	v_exp_f32_e32 v4, v4
	v_mul_f32_e32 v3, 0.5, v3
	v_add_f32_e32 v4, 1.0, v4
	v_rcp_f32_e32 v4, v4
	s_nop 0
	v_fma_f32 v4, v4, -2.0, 1.0
	v_add_f32_e32 v4, 1.0, v4
	v_mul_f32_e32 v47, v3, v4
	v_mul_f32_e32 v3, v47, v47
	v_fmac_f32_e32 v3, v46, v46
	v_add_f32_e32 v2, v3, v2
	v_lshlrev_b32_e32 v3, 16, v5
	v_mul_f32_e32 v4, 0x3d372713, v3
	v_mul_f32_e32 v4, v4, v3
	v_fma_f32 v4, v4, v3, v3
	v_mul_f32_e32 v4, 0x3f4c422a, v4
	v_add_f32_e32 v4, v4, v4
	v_mul_f32_e32 v4, 0x3fb8aa3b, v4
	v_exp_f32_e32 v4, v4
	v_mul_f32_e32 v3, 0.5, v3
	v_add_f32_e32 v4, 1.0, v4
	v_rcp_f32_e32 v4, v4
	s_nop 0
	v_fma_f32 v4, v4, -2.0, 1.0
	v_add_f32_e32 v4, 1.0, v4
	v_mul_f32_e32 v48, v3, v4
	v_and_b32_e32 v3, 0xffff0000, v5
	v_mul_f32_e32 v4, 0x3d372713, v3
	v_mul_f32_e32 v4, v4, v3
	v_fma_f32 v4, v4, v3, v3
	v_mul_f32_e32 v4, 0x3f4c422a, v4
	v_add_f32_e32 v4, v4, v4
	v_mul_f32_e32 v4, 0x3fb8aa3b, v4
	v_exp_f32_e32 v4, v4
	v_mul_f32_e32 v3, 0.5, v3
	v_add_f32_e32 v4, 1.0, v4
	v_rcp_f32_e32 v4, v4
	s_nop 0
	v_fma_f32 v4, v4, -2.0, 1.0
	v_add_f32_e32 v4, 1.0, v4
	v_mul_f32_e32 v49, v3, v4
	v_mul_f32_e32 v3, v49, v49
	v_fmac_f32_e32 v3, v48, v48
	v_and_b32_e32 v4, 64, v197
	v_add_f32_e32 v2, v3, v2
	v_xor_b32_e32 v3, 1, v197
	v_add_u32_e32 v4, 64, v4
	v_cmp_lt_i32_e32 vcc, v3, v4
	s_nop 1
	v_cndmask_b32_e32 v3, v197, v3, vcc
	v_lshlrev_b32_e32 v3, 2, v3
	ds_bpermute_b32 v3, v3, v2
	s_waitcnt lgkmcnt(0)
	v_add_f32_e32 v2, v2, v3
	v_xor_b32_e32 v3, 2, v197
	v_cmp_lt_i32_e32 vcc, v3, v4
	s_nop 1
	v_cndmask_b32_e32 v3, v197, v3, vcc
	v_lshlrev_b32_e32 v3, 2, v3
	ds_bpermute_b32 v3, v3, v2
	s_waitcnt lgkmcnt(0)
	v_add_f32_e32 v2, v2, v3
	v_fmamk_f32 v2, v2, 0x3c000000, v198
	v_rsq_f32_e32 v51, v2
	global_load_dwordx4 v[2:5], v28, s[4:5] offset:48
	global_load_dwordx4 v[6:9], v28, s[4:5] offset:32
	global_load_dwordx4 v[54:57], v28, s[4:5] offset:16
	global_load_dwordx4 v[58:61], v28, s[4:5]
	v_mul_f32_e32 v14, v14, v51
	v_mul_f32_e32 v20, v20, v51
	s_waitcnt vmcnt(0)
	v_mul_f32_e32 v14, v59, v14
	v_cvt_pk_bf16_f32 v14, v14, s0
	ds_write_b16 v19, v14 offset:272
	v_mul_f32_e32 v14, v21, v51
	v_mul_f32_e32 v14, v60, v14
	v_cvt_pk_bf16_f32 v14, v14, s0
	ds_write_b16 v19, v14 offset:544
	v_mul_f32_e32 v14, v15, v51
	v_mul_f32_e32 v14, v61, v14
	v_cvt_pk_bf16_f32 v14, v14, s0
	ds_write_b16 v19, v14 offset:816
	v_mul_f32_e32 v14, v27, v51
	v_mul_f32_e32 v14, v54, v14
	v_cvt_pk_bf16_f32 v14, v14, s0
	ds_write_b16 v19, v14 offset:1088
	v_mul_f32_e32 v14, v16, v51
	v_mul_f32_e32 v14, v55, v14
	v_cvt_pk_bf16_f32 v14, v14, s0
	ds_write_b16 v19, v14 offset:1360
	v_mul_f32_e32 v14, v39, v51
	v_mul_f32_e32 v14, v56, v14
	v_cvt_pk_bf16_f32 v14, v14, s0
	ds_write_b16 v19, v14 offset:1632
	v_mul_f32_e32 v14, v17, v51
	v_mul_f32_e32 v14, v57, v14
	v_cvt_pk_bf16_f32 v14, v14, s0
	ds_write_b16 v19, v14 offset:1904
	v_mul_f32_e32 v14, v42, v51
	v_mul_f32_e32 v6, v6, v14
	v_cvt_pk_bf16_f32 v6, v6, s0
	ds_write_b16 v19, v6 offset:2176
	v_mul_f32_e32 v6, v10, v51
	v_mul_f32_e32 v6, v7, v6
	v_cvt_pk_bf16_f32 v6, v6, s0
	ds_write_b16 v19, v6 offset:2448
	v_mul_f32_e32 v6, v45, v51
	v_mul_f32_e32 v6, v8, v6
	v_cvt_pk_bf16_f32 v6, v6, s0
	ds_write_b16 v19, v6 offset:2720
	v_mul_f32_e32 v6, v11, v51
	v_mul_f32_e32 v6, v9, v6
	v_cvt_pk_bf16_f32 v6, v6, s0
	ds_write_b16 v19, v6 offset:2992
	v_mul_f32_e32 v6, v50, v51
	v_mul_f32_e32 v2, v2, v6
	v_cvt_pk_bf16_f32 v2, v2, s0
	ds_write_b16 v19, v2 offset:3264
	v_mul_f32_e32 v2, v12, v51
	v_mul_f32_e32 v2, v3, v2
	v_cvt_pk_bf16_f32 v2, v2, s0
	ds_write_b16 v19, v2 offset:3536
	v_mul_f32_e32 v2, v52, v51
	v_mul_f32_e32 v2, v4, v2
	v_cvt_pk_bf16_f32 v2, v2, s0
	ds_write_b16 v19, v2 offset:3808
	v_mul_f32_e32 v2, v13, v51
	v_mul_f32_e32 v20, v58, v20
	v_mul_f32_e32 v2, v2, v5
	v_cvt_pk_bf16_f32 v20, v20, s0
	v_cvt_pk_bf16_f32 v2, v2, s0
	ds_write_b16 v19, v20
	ds_write_b16 v19, v2 offset:4080
	global_load_dwordx4 v[2:5], v28, s[4:5] offset:112
	global_load_dwordx4 v[6:9], v28, s[4:5] offset:96
	global_load_dwordx4 v[10:13], v28, s[4:5] offset:80
	global_load_dwordx4 v[14:17], v28, s[4:5] offset:64
	v_mul_f32_e32 v20, v53, v51
	s_mov_b32 s4, 12
	v_ashrrev_i32_e32 v27, 31, v26
	s_waitcnt vmcnt(0)
	v_mul_f32_e32 v14, v20, v14
	v_cvt_pk_bf16_f32 v14, v14, s0
	ds_write_b16 v19, v14 offset:4352
	v_mul_f32_e32 v14, v30, v51
	v_mul_f32_e32 v14, v14, v15
	v_cvt_pk_bf16_f32 v14, v14, s0
	ds_write_b16 v19, v14 offset:4624
	v_mul_f32_e32 v14, v33, v51
	v_mul_f32_e32 v14, v14, v16
	v_cvt_pk_bf16_f32 v14, v14, s0
	ds_write_b16 v19, v14 offset:4896
	v_mul_f32_e32 v14, v34, v51
	v_mul_f32_e32 v14, v14, v17
	v_cvt_pk_bf16_f32 v14, v14, s0
	ds_write_b16 v19, v14 offset:5168
	v_mul_f32_e32 v14, v35, v51
	v_mul_f32_e32 v10, v14, v10
	v_cvt_pk_bf16_f32 v10, v10, s0
	ds_write_b16 v19, v10 offset:5440
	v_mul_f32_e32 v10, v36, v51
	v_mul_f32_e32 v10, v10, v11
	v_cvt_pk_bf16_f32 v10, v10, s0
	ds_write_b16 v19, v10 offset:5712
	v_mul_f32_e32 v10, v37, v51
	v_mul_f32_e32 v10, v10, v12
	v_cvt_pk_bf16_f32 v10, v10, s0
	ds_write_b16 v19, v10 offset:5984
	v_mul_f32_e32 v10, v38, v51
	v_mul_f32_e32 v10, v10, v13
	v_cvt_pk_bf16_f32 v10, v10, s0
	ds_write_b16 v19, v10 offset:6256
	v_mul_f32_e32 v10, v40, v51
	v_mul_f32_e32 v6, v10, v6
	v_cvt_pk_bf16_f32 v6, v6, s0
	ds_write_b16 v19, v6 offset:6528
	v_mul_f32_e32 v6, v41, v51
	v_mul_f32_e32 v6, v6, v7
	v_cvt_pk_bf16_f32 v6, v6, s0
	ds_write_b16 v19, v6 offset:6800
	v_mul_f32_e32 v6, v43, v51
	v_mul_f32_e32 v6, v6, v8
	v_cvt_pk_bf16_f32 v6, v6, s0
	ds_write_b16 v19, v6 offset:7072
	v_mul_f32_e32 v6, v44, v51
	v_mul_f32_e32 v6, v6, v9
	v_cvt_pk_bf16_f32 v6, v6, s0
	ds_write_b16 v19, v6 offset:7344
	v_mul_f32_e32 v6, v46, v51
	v_mul_f32_e32 v2, v6, v2
	v_cvt_pk_bf16_f32 v2, v2, s0
	ds_write_b16 v19, v2 offset:7616
	v_mul_f32_e32 v2, v47, v51
	v_mul_f32_e32 v2, v2, v3
	v_cvt_pk_bf16_f32 v2, v2, s0
	ds_write_b16 v19, v2 offset:7888
	v_mul_f32_e32 v2, v48, v51
	v_mul_f32_e32 v2, v2, v4
	v_cvt_pk_bf16_f32 v2, v2, s0
	ds_write_b16 v19, v2 offset:8160
	v_mul_f32_e32 v2, v49, v51
	v_mul_f32_e32 v2, v2, v5
	v_cvt_pk_bf16_f32 v2, v2, s0
	ds_write_b16 v19, v2 offset:8432
	s_ashr_i32 s5, s4, 31
	s_lshl_b64 s[4:5], s[4:5], 3
	s_add_u32 s4, s0, s4
	s_addc_u32 s5, s1, s5
	s_load_dwordx2 s[8:9], s[4:5], 0x0
	v_readlane_b32 s4, v252, 23
	v_readlane_b32 s5, v252, 24
	s_or_b32 s4, s4, s7
	s_nop 0
	v_lshl_add_u64 v[2:3], s[4:5], 0, v[26:27]
	v_lshlrev_b64 v[2:3], 9, v[2:3]
	s_waitcnt lgkmcnt(0)
	v_lshl_add_u64 v[2:3], s[8:9], 0, v[2:3]
	s_movk_i32 s9, 0x110
	v_lshl_add_u64 v[20:21], v[2:3], 0, v[28:29]
	v_mul_lo_u32 v2, v26, s9
	v_add3_u32 v19, 0, v2, v0
	global_load_dwordx4 v[2:5], v[20:21], off offset:48
	global_load_dwordx4 v[6:9], v[20:21], off offset:32
	global_load_dwordx4 v[10:13], v[20:21], off offset:16
	global_load_dwordx4 v[14:17], v[20:21], off
	s_ashr_i32 s8, s6, 2
	v_and_b32_e32 v27, 15, v18
	v_lshlrev_b32_e32 v29, 2, v27
	s_waitcnt vmcnt(2)
	v_cvt_pk_bf16_f32 v6, v6, v7
	v_cvt_pk_bf16_f32 v7, v8, v9
	s_waitcnt vmcnt(0)
	v_cvt_pk_bf16_f32 v14, v14, v15
	v_cvt_pk_bf16_f32 v15, v16, v17
	v_cvt_pk_bf16_f32 v16, v10, v11
	v_cvt_pk_bf16_f32 v17, v12, v13
	v_cvt_pk_bf16_f32 v8, v2, v3
	v_cvt_pk_bf16_f32 v9, v4, v5
	ds_write_b128 v19, v[14:17] offset:34816
	ds_write_b128 v19, v[6:9] offset:34832
	global_load_dwordx4 v[2:5], v[20:21], off offset:112
	global_load_dwordx4 v[6:9], v[20:21], off offset:96
	global_load_dwordx4 v[10:13], v[20:21], off offset:80
	global_load_dwordx4 v[14:17], v[20:21], off offset:64
	s_waitcnt vmcnt(2)
	v_cvt_pk_bf16_f32 v6, v6, v7
	v_cvt_pk_bf16_f32 v7, v8, v9
	v_cvt_pk_bf16_f32 v8, v2, v3
	v_and_b32_e32 v3, 48, v18
	v_bfi_b32 v2, -16, s8, v18
	v_add_u32_e32 v30, 0, v3
	v_mad_u64_u32 v[2:3], s[6:7], v2, s9, v[30:31]
	s_waitcnt vmcnt(0)
	v_cvt_pk_bf16_f32 v14, v14, v15
	v_cvt_pk_bf16_f32 v15, v16, v17
	v_cvt_pk_bf16_f32 v16, v10, v11
	v_cvt_pk_bf16_f32 v17, v12, v13
	v_cvt_pk_bf16_f32 v9, v4, v5
	s_mov_b32 s6, 13
	ds_write_b128 v19, v[14:17] offset:34848
	ds_write_b128 v19, v[6:9] offset:34864
	s_waitcnt lgkmcnt(0)
	s_barrier
	ds_read_b128 v[14:17], v2 offset:34816
	ds_read_b128 v[10:13], v2 offset:34880
	ds_read_b128 v[6:9], v2 offset:34944
	ds_read_b128 v[2:5], v2 offset:35008
	s_ashr_i32 s7, s6, 31
	s_lshl_b64 s[6:7], s[6:7], 3
	s_add_u32 s6, s0, s6
	s_addc_u32 s7, s1, s7
	s_load_dwordx2 s[6:7], s[6:7], 0x0
	v_lshrrev_b32_e32 v18, 2, v18
	s_lshl_b64 s[4:5], s[4:5], 2
	v_and_b32_e32 v18, 12, v18
	v_and_or_b32 v42, s8, -16, v18
	s_waitcnt lgkmcnt(0)
	s_add_u32 s4, s6, s4
	s_addc_u32 s5, s7, s5
	v_ashrrev_i32_e32 v43, 31, v42
	v_lshl_add_u64 v[18:19], v[42:43], 2, s[4:5]
	global_load_dwordx4 v[18:21], v[18:19], off
	global_load_dwordx4 v[212:215], v[22:23], off
	global_load_dwordx4 v[216:219], v[22:23], off offset:16
	global_load_dwordx4 v[220:223], v[22:23], off offset:32
	global_load_dwordx4 v[224:227], v[22:23], off offset:48
	v_mad_u32_u24 v27, v27, s9, v30
	ds_read_b128 v[34:37], v27
	ds_read_b128 v[38:41], v27 offset:64
	s_waitcnt lgkmcnt(1)
	v_mfma_f32_16x16x32_bf16 v[34:37], v[14:17], v[34:37], 0
	s_movk_i32 s4, 0x210
	v_readlane_b32 s5, v254, 50
	s_waitcnt lgkmcnt(0)
	v_mfma_f32_16x16x32_bf16 v[34:37], v[10:13], v[38:41], v[34:37]
	ds_read_b128 v[38:41], v27 offset:128
	s_waitcnt lgkmcnt(0)
	v_mfma_f32_16x16x32_bf16 v[34:37], v[6:9], v[38:41], v[34:37]
	ds_read_b128 v[38:41], v27 offset:192
	s_waitcnt lgkmcnt(0)
	v_mfma_f32_16x16x32_bf16 v[34:37], v[2:5], v[38:41], v[34:37]
	s_waitcnt vmcnt(4)
	s_nop 6
	v_add_f32_e32 v33, v18, v34
	v_mul_lo_u32 v34, v42, s4
	v_add3_u32 v29, s5, v29, v34
	ds_write_b32 v29, v33
	v_add_f32_e32 v33, v19, v35
	ds_write_b32 v29, v33 offset:528
	v_add_f32_e32 v33, v20, v36
	ds_write_b32 v29, v33 offset:1056
	v_add_f32_e32 v33, v21, v37
	ds_write_b32 v29, v33 offset:1584
	ds_read_b128 v[34:37], v27 offset:4352
	ds_read_b128 v[38:41], v27 offset:4416
	s_waitcnt lgkmcnt(1)
	v_mfma_f32_16x16x32_bf16 v[34:37], v[14:17], v[34:37], 0
	s_waitcnt lgkmcnt(0)
	v_mfma_f32_16x16x32_bf16 v[34:37], v[10:13], v[38:41], v[34:37]
	ds_read_b128 v[38:41], v27 offset:4480
	s_waitcnt lgkmcnt(0)
	v_mfma_f32_16x16x32_bf16 v[34:37], v[6:9], v[38:41], v[34:37]
	ds_read_b128 v[38:41], v27 offset:4544
	s_waitcnt lgkmcnt(0)
	v_mfma_f32_16x16x32_bf16 v[34:37], v[2:5], v[38:41], v[34:37]
	s_nop 7
	v_add_f32_e32 v33, v18, v34
	ds_write_b32 v29, v33 offset:64
	v_add_f32_e32 v33, v19, v35
	ds_write_b32 v29, v33 offset:592
	v_add_f32_e32 v33, v20, v36
	ds_write_b32 v29, v33 offset:1120
	v_add_f32_e32 v33, v21, v37
	ds_write_b32 v29, v33 offset:1648
	ds_read_b128 v[34:37], v27 offset:8704
	ds_read_b128 v[38:41], v27 offset:8768
	s_waitcnt lgkmcnt(1)
	v_mfma_f32_16x16x32_bf16 v[34:37], v[14:17], v[34:37], 0
	s_waitcnt lgkmcnt(0)
	v_mfma_f32_16x16x32_bf16 v[34:37], v[10:13], v[38:41], v[34:37]
	ds_read_b128 v[38:41], v27 offset:8832
	s_waitcnt lgkmcnt(0)
	v_mfma_f32_16x16x32_bf16 v[34:37], v[6:9], v[38:41], v[34:37]
	ds_read_b128 v[38:41], v27 offset:8896
	s_waitcnt lgkmcnt(0)
	v_mfma_f32_16x16x32_bf16 v[34:37], v[2:5], v[38:41], v[34:37]
	s_nop 7
	v_add_f32_e32 v33, v18, v34
	ds_write_b32 v29, v33 offset:128
	v_add_f32_e32 v33, v19, v35
	ds_write_b32 v29, v33 offset:656
	v_add_f32_e32 v33, v20, v36
	ds_write_b32 v29, v33 offset:1184
	v_add_f32_e32 v33, v21, v37
	ds_write_b32 v29, v33 offset:1712
	v_or_b32_e32 v33, 48, v31
	v_mad_u32_u24 v33, v33, s9, v30
	ds_read_b128 v[34:37], v33
	ds_read_b128 v[38:41], v33 offset:64
	s_waitcnt lgkmcnt(1)
	v_mfma_f32_16x16x32_bf16 v[34:37], v[14:17], v[34:37], 0
	s_waitcnt lgkmcnt(0)
	v_mfma_f32_16x16x32_bf16 v[34:37], v[10:13], v[38:41], v[34:37]
	ds_read_b128 v[38:41], v33 offset:128
	s_waitcnt lgkmcnt(0)
	v_mfma_f32_16x16x32_bf16 v[34:37], v[6:9], v[38:41], v[34:37]
	ds_read_b128 v[38:41], v33 offset:192
	s_waitcnt lgkmcnt(0)
	v_mfma_f32_16x16x32_bf16 v[34:37], v[2:5], v[38:41], v[34:37]
	s_nop 7
	v_add_f32_e32 v33, v18, v34
	ds_write_b32 v29, v33 offset:192
	v_add_f32_e32 v33, v19, v35
	ds_write_b32 v29, v33 offset:720
	v_add_f32_e32 v33, v20, v36
	ds_write_b32 v29, v33 offset:1248
	v_add_f32_e32 v33, v21, v37
	ds_write_b32 v29, v33 offset:1776
	ds_read_b128 v[34:37], v27 offset:17408
	ds_read_b128 v[38:41], v27 offset:17472
	s_waitcnt lgkmcnt(1)
	v_mfma_f32_16x16x32_bf16 v[34:37], v[14:17], v[34:37], 0
	s_waitcnt lgkmcnt(0)
	v_mfma_f32_16x16x32_bf16 v[34:37], v[10:13], v[38:41], v[34:37]
	ds_read_b128 v[38:41], v27 offset:17536
	s_waitcnt lgkmcnt(0)
	v_mfma_f32_16x16x32_bf16 v[34:37], v[6:9], v[38:41], v[34:37]
	ds_read_b128 v[38:41], v27 offset:17600
	s_waitcnt lgkmcnt(0)
	v_mfma_f32_16x16x32_bf16 v[34:37], v[2:5], v[38:41], v[34:37]
	s_nop 7
	v_add_f32_e32 v33, v18, v34
	ds_write_b32 v29, v33 offset:256
	v_add_f32_e32 v33, v19, v35
	ds_write_b32 v29, v33 offset:784
	v_add_f32_e32 v33, v20, v36
	ds_write_b32 v29, v33 offset:1312
	v_add_f32_e32 v33, v21, v37
	ds_write_b32 v29, v33 offset:1840
	ds_read_b128 v[34:37], v27 offset:21760
	ds_read_b128 v[38:41], v27 offset:21824
	s_waitcnt lgkmcnt(1)
	v_mfma_f32_16x16x32_bf16 v[34:37], v[14:17], v[34:37], 0
	s_waitcnt lgkmcnt(0)
	v_mfma_f32_16x16x32_bf16 v[34:37], v[10:13], v[38:41], v[34:37]
	ds_read_b128 v[38:41], v27 offset:21888
	s_waitcnt lgkmcnt(0)
	v_mfma_f32_16x16x32_bf16 v[34:37], v[6:9], v[38:41], v[34:37]
	ds_read_b128 v[38:41], v27 offset:21952
	s_waitcnt lgkmcnt(0)
	v_mfma_f32_16x16x32_bf16 v[34:37], v[2:5], v[38:41], v[34:37]
	s_nop 7
	v_add_f32_e32 v33, v18, v34
	ds_write_b32 v29, v33 offset:320
	v_add_f32_e32 v33, v19, v35
	ds_write_b32 v29, v33 offset:848
	v_add_f32_e32 v33, v20, v36
	ds_write_b32 v29, v33 offset:1376
	v_add_f32_e32 v33, v21, v37
	ds_write_b32 v29, v33 offset:1904
	ds_read_b128 v[34:37], v27 offset:26112
	ds_read_b128 v[38:41], v27 offset:26176
	s_waitcnt lgkmcnt(1)
	v_mfma_f32_16x16x32_bf16 v[34:37], v[14:17], v[34:37], 0
	s_waitcnt lgkmcnt(0)
	v_mfma_f32_16x16x32_bf16 v[34:37], v[10:13], v[38:41], v[34:37]
	ds_read_b128 v[38:41], v27 offset:26240
	s_waitcnt lgkmcnt(0)
	v_mfma_f32_16x16x32_bf16 v[34:37], v[6:9], v[38:41], v[34:37]
	ds_read_b128 v[38:41], v27 offset:26304
	s_waitcnt lgkmcnt(0)
	v_mfma_f32_16x16x32_bf16 v[34:37], v[2:5], v[38:41], v[34:37]
	s_nop 7
	v_add_f32_e32 v27, v18, v34
	ds_write_b32 v29, v27 offset:384
	v_add_f32_e32 v27, v19, v35
	ds_write_b32 v29, v27 offset:912
	v_add_f32_e32 v27, v20, v36
	ds_write_b32 v29, v27 offset:1440
	v_add_f32_e32 v27, v21, v37
	ds_write_b32 v29, v27 offset:1968
	v_or_b32_e32 v27, 0x70, v31
	v_mad_u32_u24 v27, v27, s9, v30
	ds_read_b128 v[34:37], v27
	s_waitcnt lgkmcnt(0)
	v_mfma_f32_16x16x32_bf16 v[14:17], v[14:17], v[34:37], 0
	ds_read_b128 v[34:37], v27 offset:64
	s_waitcnt lgkmcnt(0)
	v_mfma_f32_16x16x32_bf16 v[10:13], v[10:13], v[34:37], v[14:17]
	s_nop 4
	ds_read_b128 v[14:17], v27 offset:128
	s_waitcnt lgkmcnt(0)
	v_mfma_f32_16x16x32_bf16 v[6:9], v[6:9], v[14:17], v[10:13]
	s_nop 2
	ds_read_b128 v[10:13], v27 offset:192
	s_waitcnt lgkmcnt(0)
	v_mfma_f32_16x16x32_bf16 v[2:5], v[2:5], v[10:13], v[6:9]
	s_nop 7
	v_add_f32_e32 v2, v18, v2
	ds_write_b32 v29, v2 offset:448
	v_add_f32_e32 v2, v19, v3
	ds_write_b32 v29, v2 offset:976
	v_add_f32_e32 v2, v20, v4
	ds_write_b32 v29, v2 offset:1504
	v_add_f32_e32 v2, v21, v5
	ds_write_b32 v29, v2 offset:2032
	v_mov_b64_e32 v[2:3], s[2:3]
	s_movk_i32 s2, 0xc00
	v_mad_i64_i32 v[2:3], s[2:3], v32, s2, v[2:3]
	v_lshl_add_u64 v[2:3], v[2:3], 0, s[46:47]
	v_lshl_add_u64 v[20:21], v[2:3], 0, v[0:1]
	s_mov_b64 s[2:3], 0x16300000
	v_lshl_add_u64 v[18:19], v[20:21], 0, s[2:3]
	s_mov_b32 s2, 0x7c00000
	v_add_co_u32_e32 v2, vcc, s2, v24
	s_waitcnt lgkmcnt(0)
	s_nop 0
	v_addc_co_u32_e32 v3, vcc, 0, v25, vcc
	s_barrier
	v_mul_lo_u32 v0, v26, s4
	v_add3_u32 v0, s5, v0, v28
	ds_read_b128 v[24:27], v0
	ds_read_b128 v[10:13], v0 offset:16
	ds_read_b128 v[6:9], v0 offset:32
	ds_read_b128 v[2:5], v0 offset:48
	s_mov_b32 s2, 0x16300000
	s_waitcnt vmcnt(0)
	v_lshlrev_b32_e32 v28, 16, v212
	v_and_b32_e32 v29, 0xffff0000, v212
	v_mul_f32_e32 v14, 0x3d372713, v28
	v_mul_f32_e32 v14, v14, v28
	v_mov_b32_e32 v30, v28
	v_fmac_f32_e32 v30, v14, v30
	v_mul_f32_e32 v14, 0x3f4c422a, v30
	v_add_f32_e32 v14, v14, v14
	v_mul_f32_e32 v14, 0x3fb8aa3b, v14
	v_exp_f32_e32 v14, v14
	v_mov_b32_e32 v31, v29
	v_add_f32_e32 v14, 1.0, v14
	v_rcp_f32_e32 v30, v14
	v_mul_f32_e32 v14, 0x3d372713, v29
	v_mul_f32_e32 v14, v14, v29
	v_fmac_f32_e32 v31, v14, v31
	v_mul_f32_e32 v14, 0x3f4c422a, v31
	v_add_f32_e32 v14, v14, v14
	v_mul_f32_e32 v14, 0x3fb8aa3b, v14
	v_exp_f32_e32 v14, v14
	v_pk_mul_f32 v[28:29], v[28:29], 0.5 op_sel_hi:[1,0]
	v_add_f32_e32 v14, 1.0, v14
	v_rcp_f32_e32 v31, v14
	s_nop 0
	v_pk_fma_f32 v[30:31], v[30:31], 2.0, 1.0 op_sel_hi:[1,0,0] neg_lo:[1,0,0] neg_hi:[1,0,0]
	s_nop 0
	v_pk_add_f32 v[30:31], v[30:31], 1.0 op_sel_hi:[1,0]
	s_nop 0
	v_pk_mul_f32 v[28:29], v[28:29], v[30:31]
	s_waitcnt lgkmcnt(3)
	v_pk_mul_f32 v[24:25], v[24:25], v[28:29]
	s_nop 0
	v_cvt_pk_bf16_f32 v14, v24, v25
	v_lshlrev_b32_e32 v24, 16, v213
	v_and_b32_e32 v25, 0xffff0000, v213
	v_mul_f32_e32 v15, 0x3d372713, v24
	v_mul_f32_e32 v15, v15, v24
	v_mov_b32_e32 v28, v24
	v_fmac_f32_e32 v28, v15, v28
	v_mul_f32_e32 v15, 0x3f4c422a, v28
	v_add_f32_e32 v15, v15, v15
	v_mul_f32_e32 v15, 0x3fb8aa3b, v15
	v_exp_f32_e32 v15, v15
	v_mov_b32_e32 v29, v25
	v_add_f32_e32 v15, 1.0, v15
	v_rcp_f32_e32 v28, v15
	v_mul_f32_e32 v15, 0x3d372713, v25
	v_mul_f32_e32 v15, v15, v25
	v_fmac_f32_e32 v29, v15, v29
	v_mul_f32_e32 v15, 0x3f4c422a, v29
	v_add_f32_e32 v15, v15, v15
	v_mul_f32_e32 v15, 0x3fb8aa3b, v15
	v_exp_f32_e32 v15, v15
	v_pk_mul_f32 v[24:25], v[24:25], 0.5 op_sel_hi:[1,0]
	v_add_f32_e32 v15, 1.0, v15
	v_rcp_f32_e32 v29, v15
	s_nop 0
	v_pk_fma_f32 v[28:29], v[28:29], 2.0, 1.0 op_sel_hi:[1,0,0] neg_lo:[1,0,0] neg_hi:[1,0,0]
	s_nop 0
	v_pk_add_f32 v[28:29], v[28:29], 1.0 op_sel_hi:[1,0]
	s_nop 0
	v_pk_mul_f32 v[24:25], v[24:25], v[28:29]
	s_nop 0
	v_pk_mul_f32 v[24:25], v[26:27], v[24:25]
	s_nop 0
	v_cvt_pk_bf16_f32 v15, v24, v25
	v_lshlrev_b32_e32 v24, 16, v214
	v_and_b32_e32 v25, 0xffff0000, v214
	v_mul_f32_e32 v16, 0x3d372713, v24
	v_mul_f32_e32 v16, v16, v24
	v_mov_b32_e32 v26, v24
	v_fmac_f32_e32 v26, v16, v26
	v_mul_f32_e32 v16, 0x3f4c422a, v26
	v_add_f32_e32 v16, v16, v16
	v_mul_f32_e32 v16, 0x3fb8aa3b, v16
	v_exp_f32_e32 v16, v16
	v_mov_b32_e32 v27, v25
	v_add_f32_e32 v16, 1.0, v16
	v_rcp_f32_e32 v26, v16
	v_mul_f32_e32 v16, 0x3d372713, v25
	v_mul_f32_e32 v16, v16, v25
	v_fmac_f32_e32 v27, v16, v27
	v_mul_f32_e32 v16, 0x3f4c422a, v27
	v_add_f32_e32 v16, v16, v16
	v_mul_f32_e32 v16, 0x3fb8aa3b, v16
	v_exp_f32_e32 v16, v16
	v_pk_mul_f32 v[24:25], v[24:25], 0.5 op_sel_hi:[1,0]
	v_add_f32_e32 v16, 1.0, v16
	v_rcp_f32_e32 v27, v16
	s_nop 0
	v_pk_fma_f32 v[26:27], v[26:27], 2.0, 1.0 op_sel_hi:[1,0,0] neg_lo:[1,0,0] neg_hi:[1,0,0]
	s_nop 0
	v_pk_add_f32 v[26:27], v[26:27], 1.0 op_sel_hi:[1,0]
	s_nop 0
	v_pk_mul_f32 v[24:25], v[24:25], v[26:27]
	s_waitcnt lgkmcnt(2)
	v_pk_mul_f32 v[10:11], v[10:11], v[24:25]
	s_nop 0
	v_cvt_pk_bf16_f32 v16, v10, v11
	v_lshlrev_b32_e32 v10, 16, v215
	v_and_b32_e32 v11, 0xffff0000, v215
	v_mul_f32_e32 v17, 0x3d372713, v10
	v_mul_f32_e32 v17, v17, v10
	v_mov_b32_e32 v24, v10
	v_fmac_f32_e32 v24, v17, v24
	v_mul_f32_e32 v17, 0x3f4c422a, v24
	v_add_f32_e32 v17, v17, v17
	v_mul_f32_e32 v17, 0x3fb8aa3b, v17
	v_exp_f32_e32 v17, v17
	v_mov_b32_e32 v25, v11
	v_add_f32_e32 v17, 1.0, v17
	v_rcp_f32_e32 v24, v17
	v_mul_f32_e32 v17, 0x3d372713, v11
	v_mul_f32_e32 v17, v17, v11
	v_fmac_f32_e32 v25, v17, v25
	v_mul_f32_e32 v17, 0x3f4c422a, v25
	v_add_f32_e32 v17, v17, v17
	v_mul_f32_e32 v17, 0x3fb8aa3b, v17
	v_exp_f32_e32 v17, v17
	v_pk_mul_f32 v[10:11], v[10:11], 0.5 op_sel_hi:[1,0]
	v_add_f32_e32 v17, 1.0, v17
	v_rcp_f32_e32 v25, v17
	s_nop 0
	v_pk_fma_f32 v[24:25], v[24:25], 2.0, 1.0 op_sel_hi:[1,0,0] neg_lo:[1,0,0] neg_hi:[1,0,0]
	s_nop 0
	v_pk_add_f32 v[24:25], v[24:25], 1.0 op_sel_hi:[1,0]
	s_nop 0
	v_pk_mul_f32 v[10:11], v[10:11], v[24:25]
	s_nop 0
	v_pk_mul_f32 v[10:11], v[12:13], v[10:11]
	s_nop 0
	v_cvt_pk_bf16_f32 v17, v10, v11
	v_add_co_u32_e32 v10, vcc, s2, v20
	s_nop 1
	v_addc_co_u32_e32 v11, vcc, 0, v21, vcc
	global_store_dwordx4 v[10:11], v[14:17], off
	s_nop 1
	v_lshlrev_b32_e32 v14, 16, v216
	v_and_b32_e32 v15, 0xffff0000, v216
	v_mul_f32_e32 v10, 0x3d372713, v14
	v_mul_f32_e32 v10, v10, v14
	v_mov_b32_e32 v16, v14
	v_fmac_f32_e32 v16, v10, v16
	v_mul_f32_e32 v10, 0x3f4c422a, v16
	v_add_f32_e32 v10, v10, v10
	v_mul_f32_e32 v10, 0x3fb8aa3b, v10
	v_exp_f32_e32 v10, v10
	v_mov_b32_e32 v17, v15
	v_add_f32_e32 v10, 1.0, v10
	v_rcp_f32_e32 v16, v10
	v_mul_f32_e32 v10, 0x3d372713, v15
	v_mul_f32_e32 v10, v10, v15
	v_fmac_f32_e32 v17, v10, v17
	v_mul_f32_e32 v10, 0x3f4c422a, v17
	v_add_f32_e32 v10, v10, v10
	v_mul_f32_e32 v10, 0x3fb8aa3b, v10
	v_exp_f32_e32 v10, v10
	v_pk_mul_f32 v[14:15], v[14:15], 0.5 op_sel_hi:[1,0]
	v_add_f32_e32 v10, 1.0, v10
	v_rcp_f32_e32 v17, v10
	v_lshlrev_b32_e32 v10, 16, v217
	v_and_b32_e32 v11, 0xffff0000, v217
	v_pk_fma_f32 v[16:17], v[16:17], 2.0, 1.0 op_sel_hi:[1,0,0] neg_lo:[1,0,0] neg_hi:[1,0,0]
	s_nop 0
	v_pk_add_f32 v[16:17], v[16:17], 1.0 op_sel_hi:[1,0]
	s_nop 0
	v_pk_mul_f32 v[14:15], v[14:15], v[16:17]
	s_waitcnt lgkmcnt(1)
	v_pk_mul_f32 v[6:7], v[6:7], v[14:15]
	v_mov_b32_e32 v14, v10
	v_cvt_pk_bf16_f32 v6, v6, v7
	v_mul_f32_e32 v7, 0x3d372713, v10
	v_mul_f32_e32 v7, v7, v10
	v_fmac_f32_e32 v14, v7, v14
	v_mul_f32_e32 v7, 0x3f4c422a, v14
	v_add_f32_e32 v7, v7, v7
	v_mul_f32_e32 v7, 0x3fb8aa3b, v7
	v_exp_f32_e32 v7, v7
	v_mov_b32_e32 v15, v11
	v_add_f32_e32 v7, 1.0, v7
	v_rcp_f32_e32 v14, v7
	v_mul_f32_e32 v7, 0x3d372713, v11
	v_mul_f32_e32 v7, v7, v11
	v_fmac_f32_e32 v15, v7, v15
	v_mul_f32_e32 v7, 0x3f4c422a, v15
	v_add_f32_e32 v7, v7, v7
	v_mul_f32_e32 v7, 0x3fb8aa3b, v7
	v_exp_f32_e32 v7, v7
	v_pk_mul_f32 v[10:11], v[10:11], 0.5 op_sel_hi:[1,0]
	v_add_f32_e32 v7, 1.0, v7
	v_rcp_f32_e32 v15, v7
	s_nop 0
	v_pk_fma_f32 v[14:15], v[14:15], 2.0, 1.0 op_sel_hi:[1,0,0] neg_lo:[1,0,0] neg_hi:[1,0,0]
	s_nop 0
	v_pk_add_f32 v[14:15], v[14:15], 1.0 op_sel_hi:[1,0]
	s_nop 0
	v_pk_mul_f32 v[10:11], v[10:11], v[14:15]
	s_nop 0
	v_pk_mul_f32 v[8:9], v[8:9], v[10:11]
	s_nop 0
	v_cvt_pk_bf16_f32 v7, v8, v9
	v_lshlrev_b32_e32 v8, 16, v218
	v_mul_f32_e32 v10, 0x3d372713, v8
	v_mul_f32_e32 v10, v10, v8
	v_mov_b32_e32 v11, v8
	v_and_b32_e32 v9, 0xffff0000, v218
	v_fmac_f32_e32 v11, v10, v11
	v_mul_f32_e32 v10, 0x3f4c422a, v11
	v_mul_f32_e32 v11, 0x3d372713, v9
	v_mul_f32_e32 v11, v11, v9
	v_mov_b32_e32 v12, v9
	v_fmac_f32_e32 v12, v11, v12
	v_mul_f32_e32 v11, 0x3f4c422a, v12
	v_add_f32_e32 v10, v10, v10
	v_add_f32_e32 v11, v11, v11
	v_mul_f32_e32 v10, 0x3fb8aa3b, v10
	v_mul_f32_e32 v11, 0x3fb8aa3b, v11
	v_exp_f32_e32 v10, v10
	v_exp_f32_e32 v11, v11
	v_pk_mul_f32 v[8:9], v[8:9], 0.5 op_sel_hi:[1,0]
	v_add_f32_e32 v10, 1.0, v10
	v_add_f32_e32 v11, 1.0, v11
	v_rcp_f32_e32 v10, v10
	v_rcp_f32_e32 v11, v11
	s_nop 0
	v_pk_fma_f32 v[10:11], v[10:11], 2.0, 1.0 op_sel_hi:[1,0,0] neg_lo:[1,0,0] neg_hi:[1,0,0]
	s_nop 0
	v_pk_add_f32 v[10:11], v[10:11], 1.0 op_sel_hi:[1,0]
	s_nop 0
	v_pk_mul_f32 v[8:9], v[8:9], v[10:11]
	s_waitcnt lgkmcnt(0)
	v_pk_mul_f32 v[2:3], v[2:3], v[8:9]
	s_nop 0
	v_cvt_pk_bf16_f32 v8, v2, v3
	v_lshlrev_b32_e32 v2, 16, v219
	v_mul_f32_e32 v9, 0x3d372713, v2
	v_mul_f32_e32 v9, v9, v2
	v_mov_b32_e32 v10, v2
	v_fmac_f32_e32 v10, v9, v10
	v_mul_f32_e32 v9, 0x3f4c422a, v10
	v_add_f32_e32 v9, v9, v9
	v_mul_f32_e32 v9, 0x3fb8aa3b, v9
	v_exp_f32_e32 v9, v9
	v_and_b32_e32 v3, 0xffff0000, v219
	v_mov_b32_e32 v11, v3
	v_add_f32_e32 v9, 1.0, v9
	v_rcp_f32_e32 v10, v9
	v_mul_f32_e32 v9, 0x3d372713, v3
	v_mul_f32_e32 v9, v9, v3
	v_fmac_f32_e32 v11, v9, v11
	v_mul_f32_e32 v9, 0x3f4c422a, v11
	v_add_f32_e32 v9, v9, v9
	v_mul_f32_e32 v9, 0x3fb8aa3b, v9
	v_exp_f32_e32 v9, v9
	v_pk_mul_f32 v[2:3], v[2:3], 0.5 op_sel_hi:[1,0]
	v_add_f32_e32 v9, 1.0, v9
	v_rcp_f32_e32 v11, v9
	s_nop 0
	v_pk_fma_f32 v[10:11], v[10:11], 2.0, 1.0 op_sel_hi:[1,0,0] neg_lo:[1,0,0] neg_hi:[1,0,0]
	s_nop 0
	v_pk_add_f32 v[10:11], v[10:11], 1.0 op_sel_hi:[1,0]
	s_nop 0
	v_pk_mul_f32 v[2:3], v[2:3], v[10:11]
	s_nop 0
	v_pk_mul_f32 v[2:3], v[4:5], v[2:3]
	s_nop 0
	v_cvt_pk_bf16_f32 v9, v2, v3
	global_store_dwordx4 v[18:19], v[6:9], off offset:16
	ds_read_b128 v[10:13], v0 offset:64
	ds_read_b128 v[2:5], v0 offset:80
	s_nop 1
	v_lshlrev_b32_e32 v14, 16, v220
	v_and_b32_e32 v15, 0xffff0000, v220
	v_mul_f32_e32 v6, 0x3d372713, v14
	v_mul_f32_e32 v6, v6, v14
	v_mov_b32_e32 v16, v14
	v_fmac_f32_e32 v16, v6, v16
	v_mul_f32_e32 v6, 0x3f4c422a, v16
	v_add_f32_e32 v6, v6, v6
	v_mul_f32_e32 v6, 0x3fb8aa3b, v6
	v_exp_f32_e32 v6, v6
	v_mov_b32_e32 v17, v15
	v_add_f32_e32 v6, 1.0, v6
	v_rcp_f32_e32 v16, v6
	v_mul_f32_e32 v6, 0x3d372713, v15
	v_mul_f32_e32 v6, v6, v15
	v_fmac_f32_e32 v17, v6, v17
	v_mul_f32_e32 v6, 0x3f4c422a, v17
	v_add_f32_e32 v6, v6, v6
	v_mul_f32_e32 v6, 0x3fb8aa3b, v6
	v_exp_f32_e32 v6, v6
	v_pk_mul_f32 v[14:15], v[14:15], 0.5 op_sel_hi:[1,0]
	v_add_f32_e32 v6, 1.0, v6
	v_rcp_f32_e32 v17, v6
	s_nop 0
	v_pk_fma_f32 v[16:17], v[16:17], 2.0, 1.0 op_sel_hi:[1,0,0] neg_lo:[1,0,0] neg_hi:[1,0,0]
	s_nop 0
	v_pk_add_f32 v[16:17], v[16:17], 1.0 op_sel_hi:[1,0]
	s_nop 0
	v_pk_mul_f32 v[14:15], v[14:15], v[16:17]
	s_waitcnt lgkmcnt(1)
	v_pk_mul_f32 v[10:11], v[10:11], v[14:15]
	s_nop 0
	v_cvt_pk_bf16_f32 v6, v10, v11
	v_lshlrev_b32_e32 v10, 16, v221
	v_and_b32_e32 v11, 0xffff0000, v221
	v_mul_f32_e32 v7, 0x3d372713, v10
	v_mul_f32_e32 v7, v7, v10
	v_mov_b32_e32 v14, v10
	v_fmac_f32_e32 v14, v7, v14
	v_mul_f32_e32 v7, 0x3f4c422a, v14
	v_add_f32_e32 v7, v7, v7
	v_mul_f32_e32 v7, 0x3fb8aa3b, v7
	v_exp_f32_e32 v7, v7
	v_mov_b32_e32 v15, v11
	v_add_f32_e32 v7, 1.0, v7
	v_rcp_f32_e32 v14, v7
	v_mul_f32_e32 v7, 0x3d372713, v11
	v_mul_f32_e32 v7, v7, v11
	v_fmac_f32_e32 v15, v7, v15
	v_mul_f32_e32 v7, 0x3f4c422a, v15
	v_add_f32_e32 v7, v7, v7
	v_mul_f32_e32 v7, 0x3fb8aa3b, v7
	v_exp_f32_e32 v7, v7
	v_pk_mul_f32 v[10:11], v[10:11], 0.5 op_sel_hi:[1,0]
	v_add_f32_e32 v7, 1.0, v7
	v_rcp_f32_e32 v15, v7
	s_nop 0
	v_pk_fma_f32 v[14:15], v[14:15], 2.0, 1.0 op_sel_hi:[1,0,0] neg_lo:[1,0,0] neg_hi:[1,0,0]
	s_nop 0
	v_pk_add_f32 v[14:15], v[14:15], 1.0 op_sel_hi:[1,0]
	s_nop 0
	v_pk_mul_f32 v[10:11], v[10:11], v[14:15]
	s_nop 0
	v_pk_mul_f32 v[10:11], v[12:13], v[10:11]
	s_nop 0
	v_cvt_pk_bf16_f32 v7, v10, v11
	v_lshlrev_b32_e32 v10, 16, v222
	v_and_b32_e32 v11, 0xffff0000, v222
	v_mul_f32_e32 v8, 0x3d372713, v10
	v_mul_f32_e32 v8, v8, v10
	v_mov_b32_e32 v12, v10
	v_fmac_f32_e32 v12, v8, v12
	v_mul_f32_e32 v8, 0x3f4c422a, v12
	v_add_f32_e32 v8, v8, v8
	v_mul_f32_e32 v8, 0x3fb8aa3b, v8
	v_exp_f32_e32 v8, v8
	v_mov_b32_e32 v13, v11
	v_add_f32_e32 v8, 1.0, v8
	v_rcp_f32_e32 v12, v8
	v_mul_f32_e32 v8, 0x3d372713, v11
	v_mul_f32_e32 v8, v8, v11
	v_fmac_f32_e32 v13, v8, v13
	v_mul_f32_e32 v8, 0x3f4c422a, v13
	v_add_f32_e32 v8, v8, v8
	v_mul_f32_e32 v8, 0x3fb8aa3b, v8
	v_exp_f32_e32 v8, v8
	v_pk_mul_f32 v[10:11], v[10:11], 0.5 op_sel_hi:[1,0]
	v_add_f32_e32 v8, 1.0, v8
	v_rcp_f32_e32 v13, v8
	s_nop 0
	v_pk_fma_f32 v[12:13], v[12:13], 2.0, 1.0 op_sel_hi:[1,0,0] neg_lo:[1,0,0] neg_hi:[1,0,0]
	s_nop 0
	v_pk_add_f32 v[12:13], v[12:13], 1.0 op_sel_hi:[1,0]
	s_nop 0
	v_pk_mul_f32 v[10:11], v[10:11], v[12:13]
	s_waitcnt lgkmcnt(0)
	v_pk_mul_f32 v[2:3], v[2:3], v[10:11]
	s_nop 0
	v_cvt_pk_bf16_f32 v8, v2, v3
	v_lshlrev_b32_e32 v2, 16, v223
	v_and_b32_e32 v3, 0xffff0000, v223
	v_mul_f32_e32 v9, 0x3d372713, v2
	v_mul_f32_e32 v9, v9, v2
	v_mov_b32_e32 v10, v2
	v_fmac_f32_e32 v10, v9, v10
	v_mul_f32_e32 v9, 0x3f4c422a, v10
	v_add_f32_e32 v9, v9, v9
	v_mul_f32_e32 v9, 0x3fb8aa3b, v9
	v_exp_f32_e32 v9, v9
	v_mov_b32_e32 v11, v3
	v_add_f32_e32 v9, 1.0, v9
	v_rcp_f32_e32 v10, v9
	v_mul_f32_e32 v9, 0x3d372713, v3
	v_mul_f32_e32 v9, v9, v3
	v_fmac_f32_e32 v11, v9, v11
	v_mul_f32_e32 v9, 0x3f4c422a, v11
	v_add_f32_e32 v9, v9, v9
	v_mul_f32_e32 v9, 0x3fb8aa3b, v9
	v_exp_f32_e32 v9, v9
	v_pk_mul_f32 v[2:3], v[2:3], 0.5 op_sel_hi:[1,0]
	v_add_f32_e32 v9, 1.0, v9
	v_rcp_f32_e32 v11, v9
	s_nop 0
	v_pk_fma_f32 v[10:11], v[10:11], 2.0, 1.0 op_sel_hi:[1,0,0] neg_lo:[1,0,0] neg_hi:[1,0,0]
	s_nop 0
	v_pk_add_f32 v[10:11], v[10:11], 1.0 op_sel_hi:[1,0]
	s_nop 0
	v_pk_mul_f32 v[2:3], v[2:3], v[10:11]
	s_nop 0
	v_pk_mul_f32 v[2:3], v[4:5], v[2:3]
	s_nop 0
	v_cvt_pk_bf16_f32 v9, v2, v3
	global_store_dwordx4 v[18:19], v[6:9], off offset:32
	ds_read_b128 v[10:13], v0 offset:96
	ds_read_b128 v[2:5], v0 offset:112
	s_nop 1
	v_lshlrev_b32_e32 v14, 16, v224
	v_mul_f32_e32 v0, 0x3d372713, v14
	v_and_b32_e32 v15, 0xffff0000, v224
	v_mul_f32_e32 v0, v0, v14
	v_mov_b32_e32 v6, v14
	v_fmac_f32_e32 v6, v0, v6
	v_mul_f32_e32 v0, 0x3f4c422a, v6
	v_add_f32_e32 v0, v0, v0
	v_mul_f32_e32 v0, 0x3fb8aa3b, v0
	v_exp_f32_e32 v0, v0
	v_mov_b32_e32 v6, v15
	v_add_f32_e32 v0, 1.0, v0
	v_rcp_f32_e32 v16, v0
	v_mul_f32_e32 v0, 0x3d372713, v15
	v_mul_f32_e32 v0, v0, v15
	v_fmac_f32_e32 v6, v0, v6
	v_mul_f32_e32 v0, 0x3f4c422a, v6
	v_add_f32_e32 v0, v0, v0
	v_mul_f32_e32 v0, 0x3fb8aa3b, v0
	v_exp_f32_e32 v0, v0
	v_pk_mul_f32 v[14:15], v[14:15], 0.5 op_sel_hi:[1,0]
	v_add_f32_e32 v0, 1.0, v0
	v_rcp_f32_e32 v17, v0
	s_nop 0
	v_pk_fma_f32 v[16:17], v[16:17], 2.0, 1.0 op_sel_hi:[1,0,0] neg_lo:[1,0,0] neg_hi:[1,0,0]
	s_nop 0
	v_pk_add_f32 v[16:17], v[16:17], 1.0 op_sel_hi:[1,0]
	s_nop 0
	v_pk_mul_f32 v[14:15], v[14:15], v[16:17]
	s_waitcnt lgkmcnt(1)
	v_pk_mul_f32 v[10:11], v[10:11], v[14:15]
	s_nop 0
	v_cvt_pk_bf16_f32 v6, v10, v11
	v_lshlrev_b32_e32 v10, 16, v225
	v_mul_f32_e32 v0, 0x3d372713, v10
	v_and_b32_e32 v11, 0xffff0000, v225
	v_mul_f32_e32 v0, v0, v10
	v_mov_b32_e32 v7, v10
	v_fmac_f32_e32 v7, v0, v7
	v_mul_f32_e32 v0, 0x3f4c422a, v7
	v_add_f32_e32 v0, v0, v0
	v_mul_f32_e32 v0, 0x3fb8aa3b, v0
	v_exp_f32_e32 v0, v0
	v_mov_b32_e32 v7, v11
	v_add_f32_e32 v0, 1.0, v0
	v_rcp_f32_e32 v14, v0
	v_mul_f32_e32 v0, 0x3d372713, v11
	v_mul_f32_e32 v0, v0, v11
	v_fmac_f32_e32 v7, v0, v7
	v_mul_f32_e32 v0, 0x3f4c422a, v7
	v_add_f32_e32 v0, v0, v0
	v_mul_f32_e32 v0, 0x3fb8aa3b, v0
	v_exp_f32_e32 v0, v0
	v_pk_mul_f32 v[10:11], v[10:11], 0.5 op_sel_hi:[1,0]
	v_add_f32_e32 v0, 1.0, v0
	v_rcp_f32_e32 v15, v0
	s_nop 0
	v_pk_fma_f32 v[14:15], v[14:15], 2.0, 1.0 op_sel_hi:[1,0,0] neg_lo:[1,0,0] neg_hi:[1,0,0]
	s_nop 0
	v_pk_add_f32 v[14:15], v[14:15], 1.0 op_sel_hi:[1,0]
	s_nop 0
	v_pk_mul_f32 v[10:11], v[10:11], v[14:15]
	s_nop 0
	v_pk_mul_f32 v[10:11], v[12:13], v[10:11]
	s_nop 0
	v_cvt_pk_bf16_f32 v7, v10, v11
	v_lshlrev_b32_e32 v10, 16, v226
	v_mul_f32_e32 v0, 0x3d372713, v10
	v_and_b32_e32 v11, 0xffff0000, v226
	v_mul_f32_e32 v0, v0, v10
	v_mov_b32_e32 v8, v10
	v_fmac_f32_e32 v8, v0, v8
	v_mul_f32_e32 v0, 0x3f4c422a, v8
	v_add_f32_e32 v0, v0, v0
	v_mul_f32_e32 v0, 0x3fb8aa3b, v0
	v_exp_f32_e32 v0, v0
	v_mov_b32_e32 v8, v11
	v_add_f32_e32 v0, 1.0, v0
	v_rcp_f32_e32 v12, v0
	v_mul_f32_e32 v0, 0x3d372713, v11
	v_mul_f32_e32 v0, v0, v11
	v_fmac_f32_e32 v8, v0, v8
	v_mul_f32_e32 v0, 0x3f4c422a, v8
	v_add_f32_e32 v0, v0, v0
	v_mul_f32_e32 v0, 0x3fb8aa3b, v0
	v_exp_f32_e32 v0, v0
	v_pk_mul_f32 v[10:11], v[10:11], 0.5 op_sel_hi:[1,0]
	v_add_f32_e32 v0, 1.0, v0
	v_rcp_f32_e32 v13, v0
	s_nop 0
	v_pk_fma_f32 v[12:13], v[12:13], 2.0, 1.0 op_sel_hi:[1,0,0] neg_lo:[1,0,0] neg_hi:[1,0,0]
	s_nop 0
	v_pk_add_f32 v[12:13], v[12:13], 1.0 op_sel_hi:[1,0]
	s_nop 0
	v_pk_mul_f32 v[10:11], v[10:11], v[12:13]
	s_waitcnt lgkmcnt(0)
	v_pk_mul_f32 v[2:3], v[2:3], v[10:11]
	s_nop 0
	v_cvt_pk_bf16_f32 v8, v2, v3
	v_lshlrev_b32_e32 v2, 16, v227
	v_mul_f32_e32 v0, 0x3d372713, v2
	v_and_b32_e32 v3, 0xffff0000, v227
	v_mul_f32_e32 v0, v0, v2
	v_mov_b32_e32 v9, v2
	v_fmac_f32_e32 v9, v0, v9
	v_mul_f32_e32 v0, 0x3f4c422a, v9
	v_add_f32_e32 v0, v0, v0
	v_mul_f32_e32 v0, 0x3fb8aa3b, v0
	v_exp_f32_e32 v0, v0
	v_mov_b32_e32 v9, v3
	v_add_f32_e32 v0, 1.0, v0
	v_rcp_f32_e32 v10, v0
	v_mul_f32_e32 v0, 0x3d372713, v3
	v_mul_f32_e32 v0, v0, v3
	v_fmac_f32_e32 v9, v0, v9
	v_mul_f32_e32 v0, 0x3f4c422a, v9
	v_add_f32_e32 v0, v0, v0
	v_mul_f32_e32 v0, 0x3fb8aa3b, v0
	v_exp_f32_e32 v0, v0
	v_pk_mul_f32 v[2:3], v[2:3], 0.5 op_sel_hi:[1,0]
	v_add_f32_e32 v0, 1.0, v0
	v_rcp_f32_e32 v11, v0
	s_nop 0
	v_pk_fma_f32 v[10:11], v[10:11], 2.0, 1.0 op_sel_hi:[1,0,0] neg_lo:[1,0,0] neg_hi:[1,0,0]
	s_nop 0
	v_pk_add_f32 v[10:11], v[10:11], 1.0 op_sel_hi:[1,0]
	s_nop 0
	v_pk_mul_f32 v[2:3], v[2:3], v[10:11]
	s_nop 0
	v_pk_mul_f32 v[2:3], v[4:5], v[2:3]
	s_nop 0
	v_cvt_pk_bf16_f32 v9, v2, v3
	global_store_dwordx4 v[18:19], v[6:9], off offset:48
	s_barrier
	s_branch .LBB0_428
